# grid barriers: a follower workgroup issues its acquire invalidate (buffer_inv sc1) when it arrives, before polling, instead of after the release (its L1 stays untouched while it polls; the XCC leader'
# speedup vs baseline: 1.0777x; 1.0086x over previous
; __device__ __forceinline__ unsigned xb_ld(unsigned* p)              { return __hip_atomic_load(p, __ATOMIC_RELAXED, __HIP_MEMORY_SCOPE_AGENT); }
; #define XB_SPIN(cond, bar) do { unsigned _sp = 0; while (cond) { __builtin_amdgcn_s_sleep(1); \
;     if ((++_sp & 255u) == 0u) { if (xb_ld(&(bar)[XB_TMO])) break; if (_sp > XB_SPIN_CAP) { atomicAdd(&(bar)[XB_TMO], 1u); break; } } } } while (0)
; __device__ __forceinline__ void xcd_barrier(const XcdBarrier& b, const int WID) {
;     ...
;         } else {
;             XB_SPIN(xb_ld(&bar[XB_XGEN(b.x)]) == gen, bar);
;             __builtin_amdgcn_fence(__ATOMIC_ACQUIRE, "agent");
;             asm volatile("s_waitcnt vmcnt(0)" ::: "memory");
;         }
.Lgb_follower:
	buffer_inv sc1
	v_mov_b32_e32 v2, s9
	s_mov_b32 s98, 0

; __device__ __forceinline__ unsigned xb_ld(unsigned* p)              { return __hip_atomic_load(p, __ATOMIC_RELAXED, __HIP_MEMORY_SCOPE_AGENT); }
; #define XB_SPIN(cond, bar) do { unsigned _sp = 0; while (cond) { __builtin_amdgcn_s_sleep(1); \
;     if ((++_sp & 255u) == 0u) { if (xb_ld(&(bar)[XB_TMO])) break; if (_sp > XB_SPIN_CAP) { atomicAdd(&(bar)[XB_TMO], 1u); break; } } } } while (0)
; __device__ __forceinline__ void xcd_barrier(const XcdBarrier& b, const int WID) {
;     ...
;             XB_SPIN(xb_ld(&bar[XB_XGEN(b.x)]) == gen, bar);
;             __builtin_amdgcn_fence(__ATOMIC_ACQUIRE, "agent");
;             asm volatile("s_waitcnt vmcnt(0)" ::: "memory");
;         }
.Lgb_xdone:
	s_waitcnt vmcnt(0)
.Lgb_done:
	s_waitcnt lgkmcnt(0)

; __device__ __forceinline__ unsigned xb_ld(unsigned* p)              { return __hip_atomic_load(p, __ATOMIC_RELAXED, __HIP_MEMORY_SCOPE_AGENT); }
; __device__ __forceinline__ unsigned xb_add(unsigned* p, unsigned v) { return __hip_atomic_fetch_add(p, v, __ATOMIC_RELAXED, __HIP_MEMORY_SCOPE_AGENT); }
; #define XB_SPIN(cond, bar) do { unsigned _sp = 0; while (cond) { __builtin_amdgcn_s_sleep(1); \
;     if ((++_sp & 255u) == 0u) { if (xb_ld(&(bar)[XB_TMO])) break; if (_sp > XB_SPIN_CAP) { atomicAdd(&(bar)[XB_TMO], 1u); break; } } } } while (0)
; __device__ __forceinline__ void xcd_barrier(const XcdBarrier& b, const int WID) {
;     ...
;         const unsigned old = xb_add(&bar[XB_XSUB(b.x)], 1u);
;         const unsigned gen = old / nloc;
;         if (old + 1u == (gen + 1u) * nloc) {
;     ...
;         } else {
;             XB_SPIN(xb_ld(&bar[XB_XGEN(b.x)]) == gen, bar);
;             __builtin_amdgcn_fence(__ATOMIC_ACQUIRE, "agent");
.LBB0_113:
	s_or_b64 exec, exec, s[8:9]
	v_cvt_f32_u32_e32 v4, v2
	s_waitcnt vmcnt(0)
	v_readfirstlane_b32 s8, v3
	v_sub_u32_e32 v3, 0, v2
	v_rcp_iflag_f32_e32 v4, v4
	v_add_u32_e32 v5, s8, v1
	v_mul_f32_e32 v4, 0x4f7ffffe, v4
	v_cvt_u32_f32_e32 v4, v4
	v_mul_lo_u32 v1, v3, v4
	v_mul_hi_u32 v1, v4, v1
	v_add_u32_e32 v1, v4, v1
	v_mul_hi_u32 v1, v5, v1
	v_mul_lo_u32 v3, v1, v2
	v_sub_u32_e32 v3, v5, v3
	v_add_u32_e32 v4, 1, v1
	v_cmp_ge_u32_e32 vcc, v3, v2
	s_nop 1
	v_cndmask_b32_e32 v1, v1, v4, vcc
	v_sub_u32_e32 v4, v3, v2
	v_cndmask_b32_e32 v3, v3, v4, vcc
	v_add_u32_e32 v4, 1, v1
	v_cmp_ge_u32_e32 vcc, v3, v2
	v_add_u32_e32 v3, 1, v5
	s_nop 0
	v_cndmask_b32_e32 v1, v1, v4, vcc
	v_mul_lo_u32 v4, v2, v1
	v_add_u32_e32 v2, v4, v2
	v_cmp_ne_u32_e32 vcc, v3, v2
	s_and_saveexec_b64 s[8:9], vcc
	s_xor_b64 s[8:9], exec, s[8:9]
	s_cbranch_execz .LBB0_127
	buffer_inv sc1
	v_readlane_b32 s10, v251, 29
	s_waitcnt lgkmcnt(0)
	v_mov_b32_e32 v0, 0
	v_readlane_b32 s11, v251, 30
	s_nop 4
	global_load_dword v2, v0, s[10:11] sc1
	s_waitcnt vmcnt(0)
	v_cmp_eq_u32_e32 vcc, v2, v1
	s_and_saveexec_b64 s[10:11], vcc
	s_cbranch_execz .LBB0_126
	s_mov_b32 s22, 1
	s_mov_b64 s[12:13], 0
	s_branch .LBB0_117

; __device__ __forceinline__ unsigned xb_ld(unsigned* p)              { return __hip_atomic_load(p, __ATOMIC_RELAXED, __HIP_MEMORY_SCOPE_AGENT); }
; #define XB_SPIN(cond, bar) do { unsigned _sp = 0; while (cond) { __builtin_amdgcn_s_sleep(1); \
;     if ((++_sp & 255u) == 0u) { if (xb_ld(&(bar)[XB_TMO])) break; if (_sp > XB_SPIN_CAP) { atomicAdd(&(bar)[XB_TMO], 1u); break; } } } } while (0)
; __device__ __forceinline__ void xcd_barrier(const XcdBarrier& b, const int WID) {
;     ...
;             XB_SPIN(xb_ld(&bar[XB_XGEN(b.x)]) == gen, bar);
;             __builtin_amdgcn_fence(__ATOMIC_ACQUIRE, "agent");
;             asm volatile("s_waitcnt vmcnt(0)" ::: "memory");
;         }
.LBB0_126:
	s_or_b64 exec, exec, s[10:11]
	s_waitcnt vmcnt(0)
	s_waitcnt vmcnt(0)

; __device__ __forceinline__ unsigned xb_ld(unsigned* p)              { return __hip_atomic_load(p, __ATOMIC_RELAXED, __HIP_MEMORY_SCOPE_AGENT); }
; __device__ __forceinline__ unsigned xb_add(unsigned* p, unsigned v) { return __hip_atomic_fetch_add(p, v, __ATOMIC_RELAXED, __HIP_MEMORY_SCOPE_AGENT); }
; #define XB_SPIN(cond, bar) do { unsigned _sp = 0; while (cond) { __builtin_amdgcn_s_sleep(1); \
;     if ((++_sp & 255u) == 0u) { if (xb_ld(&(bar)[XB_TMO])) break; if (_sp > XB_SPIN_CAP) { atomicAdd(&(bar)[XB_TMO], 1u); break; } } } } while (0)
; __device__ __forceinline__ void xcd_barrier(const XcdBarrier& b, const int WID) {
;     ...
;         const unsigned old = xb_add(&bar[XB_XSUB(b.x)], 1u);
;         const unsigned gen = old / nloc;
;         if (old + 1u == (gen + 1u) * nloc) {
;     ...
;         } else {
;             XB_SPIN(xb_ld(&bar[XB_XGEN(b.x)]) == gen, bar);
;             __builtin_amdgcn_fence(__ATOMIC_ACQUIRE, "agent");
.LBB0_176:
	s_or_b64 exec, exec, s[4:5]
	v_cvt_f32_u32_e32 v4, v2
	s_waitcnt vmcnt(0)
	v_readfirstlane_b32 s4, v3
	v_sub_u32_e32 v3, 0, v2
	v_rcp_iflag_f32_e32 v4, v4
	v_add_u32_e32 v5, s4, v1
	v_mul_f32_e32 v4, 0x4f7ffffe, v4
	v_cvt_u32_f32_e32 v4, v4
	v_mul_lo_u32 v1, v3, v4
	v_mul_hi_u32 v1, v4, v1
	v_add_u32_e32 v1, v4, v1
	v_mul_hi_u32 v1, v5, v1
	v_mul_lo_u32 v3, v1, v2
	v_sub_u32_e32 v3, v5, v3
	v_add_u32_e32 v4, 1, v1
	v_cmp_ge_u32_e32 vcc, v3, v2
	s_nop 1
	v_cndmask_b32_e32 v1, v1, v4, vcc
	v_sub_u32_e32 v4, v3, v2
	v_cndmask_b32_e32 v3, v3, v4, vcc
	v_add_u32_e32 v4, 1, v1
	v_cmp_ge_u32_e32 vcc, v3, v2
	v_add_u32_e32 v3, 1, v5
	s_nop 0
	v_cndmask_b32_e32 v1, v1, v4, vcc
	v_mul_lo_u32 v4, v2, v1
	v_add_u32_e32 v2, v4, v2
	v_cmp_ne_u32_e32 vcc, v3, v2
	s_and_saveexec_b64 s[4:5], vcc
	s_xor_b64 s[4:5], exec, s[4:5]
	s_cbranch_execz .LBB0_190
	buffer_inv sc1
	v_readlane_b32 s8, v251, 29
	s_waitcnt lgkmcnt(0)
	v_mov_b32_e32 v0, 0
	v_readlane_b32 s9, v251, 30
	s_nop 4
	global_load_dword v2, v0, s[8:9] sc1
	s_waitcnt vmcnt(0)
	v_cmp_eq_u32_e32 vcc, v2, v1
	s_and_saveexec_b64 s[8:9], vcc
	s_cbranch_execz .LBB0_189
	s_mov_b32 s17, 1
	s_mov_b64 s[10:11], 0
	s_branch .LBB0_180

; __device__ __forceinline__ unsigned xb_ld(unsigned* p)              { return __hip_atomic_load(p, __ATOMIC_RELAXED, __HIP_MEMORY_SCOPE_AGENT); }
; #define XB_SPIN(cond, bar) do { unsigned _sp = 0; while (cond) { __builtin_amdgcn_s_sleep(1); \
;     if ((++_sp & 255u) == 0u) { if (xb_ld(&(bar)[XB_TMO])) break; if (_sp > XB_SPIN_CAP) { atomicAdd(&(bar)[XB_TMO], 1u); break; } } } } while (0)
; __device__ __forceinline__ void xcd_barrier(const XcdBarrier& b, const int WID) {
;     ...
;             XB_SPIN(xb_ld(&bar[XB_XGEN(b.x)]) == gen, bar);
;             __builtin_amdgcn_fence(__ATOMIC_ACQUIRE, "agent");
;             asm volatile("s_waitcnt vmcnt(0)" ::: "memory");
;         }
.LBB0_189:
	s_or_b64 exec, exec, s[8:9]
	s_waitcnt vmcnt(0)
	s_waitcnt vmcnt(0)

; __device__ __forceinline__ unsigned xb_ld(unsigned* p)              { return __hip_atomic_load(p, __ATOMIC_RELAXED, __HIP_MEMORY_SCOPE_AGENT); }
; __device__ __forceinline__ unsigned xb_add(unsigned* p, unsigned v) { return __hip_atomic_fetch_add(p, v, __ATOMIC_RELAXED, __HIP_MEMORY_SCOPE_AGENT); }
; #define XB_SPIN(cond, bar) do { unsigned _sp = 0; while (cond) { __builtin_amdgcn_s_sleep(1); \
;     if ((++_sp & 255u) == 0u) { if (xb_ld(&(bar)[XB_TMO])) break; if (_sp > XB_SPIN_CAP) { atomicAdd(&(bar)[XB_TMO], 1u); break; } } } } while (0)
; __device__ __forceinline__ void xcd_barrier(const XcdBarrier& b, const int WID) {
;     ...
;         const unsigned old = xb_add(&bar[XB_XSUB(b.x)], 1u);
;         const unsigned gen = old / nloc;
;         if (old + 1u == (gen + 1u) * nloc) {
;     ...
;         } else {
;             XB_SPIN(xb_ld(&bar[XB_XGEN(b.x)]) == gen, bar);
;             __builtin_amdgcn_fence(__ATOMIC_ACQUIRE, "agent");
.LBB0_621:
	s_or_b64 exec, exec, s[2:3]
	v_cvt_f32_u32_e32 v4, v2
	s_waitcnt vmcnt(0)
	v_readfirstlane_b32 s2, v3
	v_sub_u32_e32 v3, 0, v2
	v_rcp_iflag_f32_e32 v4, v4
	v_add_u32_e32 v5, s2, v1
	v_mul_f32_e32 v4, 0x4f7ffffe, v4
	v_cvt_u32_f32_e32 v4, v4
	v_mul_lo_u32 v1, v3, v4
	v_mul_hi_u32 v1, v4, v1
	v_add_u32_e32 v1, v4, v1
	v_mul_hi_u32 v1, v5, v1
	v_mul_lo_u32 v3, v1, v2
	v_sub_u32_e32 v3, v5, v3
	v_add_u32_e32 v4, 1, v1
	v_cmp_ge_u32_e32 vcc, v3, v2
	s_nop 1
	v_cndmask_b32_e32 v1, v1, v4, vcc
	v_sub_u32_e32 v4, v3, v2
	v_cndmask_b32_e32 v3, v3, v4, vcc
	v_add_u32_e32 v4, 1, v1
	v_cmp_ge_u32_e32 vcc, v3, v2
	v_add_u32_e32 v3, 1, v5
	s_nop 0
	v_cndmask_b32_e32 v1, v1, v4, vcc
	v_mul_lo_u32 v4, v2, v1
	v_add_u32_e32 v2, v4, v2
	v_cmp_ne_u32_e32 vcc, v3, v2
	s_and_saveexec_b64 s[2:3], vcc
	s_xor_b64 s[2:3], exec, s[2:3]
	s_cbranch_execz .LBB0_635
	buffer_inv sc1
	v_readlane_b32 s4, v251, 29
	s_waitcnt lgkmcnt(0)
	v_mov_b32_e32 v0, 0
	v_readlane_b32 s5, v251, 30
	s_nop 4
	global_load_dword v2, v0, s[4:5] sc1
	s_waitcnt vmcnt(0)
	v_cmp_eq_u32_e32 vcc, v2, v1
	s_and_saveexec_b64 s[4:5], vcc
	s_cbranch_execz .LBB0_634
	s_mov_b32 s18, 1
	s_mov_b64 s[8:9], 0
	s_branch .LBB0_625

; __device__ __forceinline__ unsigned xb_ld(unsigned* p)              { return __hip_atomic_load(p, __ATOMIC_RELAXED, __HIP_MEMORY_SCOPE_AGENT); }
; #define XB_SPIN(cond, bar) do { unsigned _sp = 0; while (cond) { __builtin_amdgcn_s_sleep(1); \
;     if ((++_sp & 255u) == 0u) { if (xb_ld(&(bar)[XB_TMO])) break; if (_sp > XB_SPIN_CAP) { atomicAdd(&(bar)[XB_TMO], 1u); break; } } } } while (0)
; __device__ __forceinline__ void xcd_barrier(const XcdBarrier& b, const int WID) {
;     ...
;             XB_SPIN(xb_ld(&bar[XB_XGEN(b.x)]) == gen, bar);
;             __builtin_amdgcn_fence(__ATOMIC_ACQUIRE, "agent");
;             asm volatile("s_waitcnt vmcnt(0)" ::: "memory");
;         }
.LBB0_634:
	s_or_b64 exec, exec, s[4:5]
	s_waitcnt vmcnt(0)
	s_waitcnt vmcnt(0)

; __device__ __forceinline__ unsigned xb_ld(unsigned* p)              { return __hip_atomic_load(p, __ATOMIC_RELAXED, __HIP_MEMORY_SCOPE_AGENT); }
; __device__ __forceinline__ unsigned xb_add(unsigned* p, unsigned v) { return __hip_atomic_fetch_add(p, v, __ATOMIC_RELAXED, __HIP_MEMORY_SCOPE_AGENT); }
; #define XB_SPIN(cond, bar) do { unsigned _sp = 0; while (cond) { __builtin_amdgcn_s_sleep(1); \
;     if ((++_sp & 255u) == 0u) { if (xb_ld(&(bar)[XB_TMO])) break; if (_sp > XB_SPIN_CAP) { atomicAdd(&(bar)[XB_TMO], 1u); break; } } } } while (0)
; __device__ __forceinline__ void xcd_barrier(const XcdBarrier& b, const int WID) {
;     ...
;         const unsigned old = xb_add(&bar[XB_XSUB(b.x)], 1u);
;         const unsigned gen = old / nloc;
;         if (old + 1u == (gen + 1u) * nloc) {
;     ...
;         } else {
;             XB_SPIN(xb_ld(&bar[XB_XGEN(b.x)]) == gen, bar);
;             __builtin_amdgcn_fence(__ATOMIC_ACQUIRE, "agent");
.LBB0_730:
	s_or_b64 exec, exec, s[2:3]
	v_cvt_f32_u32_e32 v4, v2
	s_waitcnt vmcnt(0)
	v_readfirstlane_b32 s2, v3
	v_sub_u32_e32 v3, 0, v2
	v_rcp_iflag_f32_e32 v4, v4
	v_add_u32_e32 v5, s2, v1
	v_mul_f32_e32 v4, 0x4f7ffffe, v4
	v_cvt_u32_f32_e32 v4, v4
	v_mul_lo_u32 v1, v3, v4
	v_mul_hi_u32 v1, v4, v1
	v_add_u32_e32 v1, v4, v1
	v_mul_hi_u32 v1, v5, v1
	v_mul_lo_u32 v3, v1, v2
	v_sub_u32_e32 v3, v5, v3
	v_add_u32_e32 v4, 1, v1
	v_cmp_ge_u32_e32 vcc, v3, v2
	s_nop 1
	v_cndmask_b32_e32 v1, v1, v4, vcc
	v_sub_u32_e32 v4, v3, v2
	v_cndmask_b32_e32 v3, v3, v4, vcc
	v_add_u32_e32 v4, 1, v1
	v_cmp_ge_u32_e32 vcc, v3, v2
	v_add_u32_e32 v3, 1, v5
	s_nop 0
	v_cndmask_b32_e32 v1, v1, v4, vcc
	v_mul_lo_u32 v4, v2, v1
	v_add_u32_e32 v2, v4, v2
	v_cmp_ne_u32_e32 vcc, v3, v2
	s_and_saveexec_b64 s[2:3], vcc
	s_xor_b64 s[2:3], exec, s[2:3]
	s_cbranch_execz .LBB0_744
	buffer_inv sc1
	v_readlane_b32 s8, v251, 29
	s_waitcnt lgkmcnt(0)
	v_mov_b32_e32 v0, 0
	v_readlane_b32 s9, v251, 30
	s_nop 4
	global_load_dword v2, v0, s[8:9] sc1
	s_waitcnt vmcnt(0)
	v_cmp_eq_u32_e32 vcc, v2, v1
	s_and_saveexec_b64 s[8:9], vcc
	s_cbranch_execz .LBB0_743
	s_mov_b32 s25, 1
	s_mov_b64 s[10:11], 0
	s_branch .LBB0_734

; __device__ __forceinline__ unsigned xb_ld(unsigned* p)              { return __hip_atomic_load(p, __ATOMIC_RELAXED, __HIP_MEMORY_SCOPE_AGENT); }
; __device__ __forceinline__ unsigned xb_add(unsigned* p, unsigned v) { return __hip_atomic_fetch_add(p, v, __ATOMIC_RELAXED, __HIP_MEMORY_SCOPE_AGENT); }
; #define XB_SPIN(cond, bar) do { unsigned _sp = 0; while (cond) { __builtin_amdgcn_s_sleep(1); \
;     if ((++_sp & 255u) == 0u) { if (xb_ld(&(bar)[XB_TMO])) break; if (_sp > XB_SPIN_CAP) { atomicAdd(&(bar)[XB_TMO], 1u); break; } } } } while (0)
; __device__ __forceinline__ void xcd_barrier(const XcdBarrier& b, const int WID) {
;     ...
;         const unsigned old = xb_add(&bar[XB_XSUB(b.x)], 1u);
;         const unsigned gen = old / nloc;
;         if (old + 1u == (gen + 1u) * nloc) {
;     ...
;         } else {
;             XB_SPIN(xb_ld(&bar[XB_XGEN(b.x)]) == gen, bar);
;             __builtin_amdgcn_fence(__ATOMIC_ACQUIRE, "agent");
.LBB0_834:
	s_or_b64 exec, exec, s[8:9]
	v_cvt_f32_u32_e32 v4, v2
	s_waitcnt vmcnt(0)
	v_readfirstlane_b32 s8, v3
	v_sub_u32_e32 v3, 0, v2
	v_rcp_iflag_f32_e32 v4, v4
	v_add_u32_e32 v5, s8, v1
	v_mul_f32_e32 v4, 0x4f7ffffe, v4
	v_cvt_u32_f32_e32 v4, v4
	v_mul_lo_u32 v1, v3, v4
	v_mul_hi_u32 v1, v4, v1
	v_add_u32_e32 v1, v4, v1
	v_mul_hi_u32 v1, v5, v1
	v_mul_lo_u32 v3, v1, v2
	v_sub_u32_e32 v3, v5, v3
	v_add_u32_e32 v4, 1, v1
	v_cmp_ge_u32_e32 vcc, v3, v2
	s_nop 1
	v_cndmask_b32_e32 v1, v1, v4, vcc
	v_sub_u32_e32 v4, v3, v2
	v_cndmask_b32_e32 v3, v3, v4, vcc
	v_add_u32_e32 v4, 1, v1
	v_cmp_ge_u32_e32 vcc, v3, v2
	v_add_u32_e32 v3, 1, v5
	s_nop 0
	v_cndmask_b32_e32 v1, v1, v4, vcc
	v_mul_lo_u32 v4, v2, v1
	v_add_u32_e32 v2, v4, v2
	v_cmp_ne_u32_e32 vcc, v3, v2
	s_and_saveexec_b64 s[8:9], vcc
	s_xor_b64 s[8:9], exec, s[8:9]
	s_cbranch_execz .LBB0_848
	buffer_inv sc1
	v_readlane_b32 s10, v251, 29
	s_waitcnt lgkmcnt(0)
	v_mov_b32_e32 v0, 0
	v_readlane_b32 s11, v251, 30
	s_nop 4
	global_load_dword v2, v0, s[10:11] sc1
	s_waitcnt vmcnt(0)
	v_cmp_eq_u32_e32 vcc, v2, v1
	s_and_saveexec_b64 s[10:11], vcc
	s_cbranch_execz .LBB0_847
	s_mov_b32 s25, 1
	s_mov_b64 s[12:13], 0
	s_branch .LBB0_838

; __device__ __forceinline__ unsigned xb_ld(unsigned* p)              { return __hip_atomic_load(p, __ATOMIC_RELAXED, __HIP_MEMORY_SCOPE_AGENT); }
; __device__ __forceinline__ unsigned xb_add(unsigned* p, unsigned v) { return __hip_atomic_fetch_add(p, v, __ATOMIC_RELAXED, __HIP_MEMORY_SCOPE_AGENT); }
; #define XB_SPIN(cond, bar) do { unsigned _sp = 0; while (cond) { __builtin_amdgcn_s_sleep(1); \
;     if ((++_sp & 255u) == 0u) { if (xb_ld(&(bar)[XB_TMO])) break; if (_sp > XB_SPIN_CAP) { atomicAdd(&(bar)[XB_TMO], 1u); break; } } } } while (0)
; __device__ __forceinline__ void xcd_barrier(const XcdBarrier& b, const int WID) {
;     ...
;         const unsigned old = xb_add(&bar[XB_XSUB(b.x)], 1u);
;         const unsigned gen = old / nloc;
;         if (old + 1u == (gen + 1u) * nloc) {
;             __builtin_amdgcn_fence(__ATOMIC_RELEASE, "agent");
;             asm volatile("s_waitcnt vmcnt(0)" ::: "memory");
;             const unsigned og = xb_add(&bar[XB_TOP], 1u);
;             const unsigned tg = og / nx;
;             if (og + 1u == (tg + 1u) * nx) xb_add(&bar[XB_TOPGEN], 1u);
;             else XB_SPIN(xb_ld(&bar[XB_TOPGEN]) == tg, bar);
;             __builtin_amdgcn_fence(__ATOMIC_ACQUIRE, "agent");
;             xb_add(&bar[XB_XGEN(b.x)], 1u);
;             asm volatile("s_waitcnt vmcnt(0)" ::: "memory");
;         } else {
;             XB_SPIN(xb_ld(&bar[XB_XGEN(b.x)]) == gen, bar);
;             __builtin_amdgcn_fence(__ATOMIC_ACQUIRE, "agent");
.LBB0_1045:
	s_or_b64 exec, exec, s[2:3]
	v_cvt_f32_u32_e32 v4, v2
	s_waitcnt vmcnt(0)
	v_readfirstlane_b32 s2, v3
	v_sub_u32_e32 v3, 0, v2
	v_rcp_iflag_f32_e32 v4, v4
	v_add_u32_e32 v5, s2, v1
	v_mul_f32_e32 v4, 0x4f7ffffe, v4
	v_cvt_u32_f32_e32 v4, v4
	v_mul_lo_u32 v1, v3, v4
	v_mul_hi_u32 v1, v4, v1
	v_add_u32_e32 v1, v4, v1
	v_mul_hi_u32 v1, v5, v1
	v_mul_lo_u32 v3, v1, v2
	v_sub_u32_e32 v3, v5, v3
	v_add_u32_e32 v4, 1, v1
	v_cmp_ge_u32_e32 vcc, v3, v2
	s_nop 1
	v_cndmask_b32_e32 v1, v1, v4, vcc
	v_sub_u32_e32 v4, v3, v2
	v_cndmask_b32_e32 v3, v3, v4, vcc
	v_add_u32_e32 v4, 1, v1
	v_cmp_ge_u32_e32 vcc, v3, v2
	v_add_u32_e32 v3, 1, v5
	s_nop 0
	v_cndmask_b32_e32 v1, v1, v4, vcc
	v_mul_lo_u32 v4, v2, v1
	v_add_u32_e32 v2, v4, v2
	v_cmp_ne_u32_e32 vcc, v3, v2
	s_and_saveexec_b64 s[2:3], vcc
	s_xor_b64 s[2:3], exec, s[2:3]
	s_cbranch_execz .LBB0_1059
	buffer_inv sc1
	v_readlane_b32 s4, v251, 29
	s_waitcnt lgkmcnt(0)
	v_mov_b32_e32 v0, 0
	v_readlane_b32 s5, v251, 30
	s_nop 4
	global_load_dword v2, v0, s[4:5] sc1
	s_waitcnt vmcnt(0)
	v_cmp_eq_u32_e32 vcc, v2, v1
	s_and_saveexec_b64 s[4:5], vcc
	s_cbranch_execz .LBB0_1058
	s_mov_b32 s16, 1
	s_mov_b64 s[6:7], 0
	s_branch .LBB0_1049
